# grid-barrier arrival: for 32 WGs per XCD the last-arriver test uses shift and mask instead of the integer division
# baseline (speedup 1.0000x reference)
; __device__ __forceinline__ unsigned xb_add(unsigned* p, unsigned v) { return __hip_atomic_fetch_add(p, v, __ATOMIC_RELAXED, __HIP_MEMORY_SCOPE_AGENT); }
; __device__ __forceinline__ void xcd_barrier(const XcdBarrier& b) {
;     ...
;         const unsigned old = xb_add(&bar[XB_XSUB(bx_)], 1u);
;         const unsigned gen = old / nloc;
;         if (old + 1u == (gen + 1u) * nloc) {
.LBB0_697:
	s_lshl_b32 s4, s36, 6
	s_add_i32 s84, s4, 0x500
	s_lshl_b64 s[0:1], s[84:85], 2
	s_add_u32 s0, s34, s0
	s_addc_u32 s1, s35, s1
	v_mov_b64_e32 v[8:9], s[0:1]
	v_mov_b32_e32 v5, 1
	flat_atomic_add v5, v[8:9], v5 sc0
	v_cvt_f32_u32_e32 v7, v6
	v_sub_u32_e32 v8, 0, v6
	v_rcp_iflag_f32_e32 v7, v7
	s_nop 0
	v_mul_f32_e32 v7, 0x4f7ffffe, v7
	v_cvt_u32_f32_e32 v7, v7
	v_mul_lo_u32 v8, v8, v7
	v_mul_hi_u32 v8, v7, v8
	v_add_u32_e32 v7, v7, v8
	s_waitcnt vmcnt(0) lgkmcnt(0)
	v_cmp_eq_u32_e32 vcc, 32, v6
	s_cbranch_vccz .Ldv0_slow
	v_add_u32_e32 v8, 1, v5
	v_lshrrev_b32_e32 v5, 5, v5
	v_add_u32_e32 v5, 1, v5
	v_and_b32_e32 v9, 31, v8
	v_cmp_eq_u32_e32 vcc, 0, v9
	s_branch .Ldv0_join
.Ldv0_slow:
	v_mul_hi_u32 v7, v5, v7
	v_mul_lo_u32 v8, v7, v6
	v_sub_u32_e32 v8, v5, v8
	v_add_u32_e32 v9, 1, v7
	v_cmp_ge_u32_e32 vcc, v8, v6
	s_nop 1
	v_cndmask_b32_e32 v7, v7, v9, vcc
	v_sub_u32_e32 v9, v8, v6
	v_cndmask_b32_e32 v8, v8, v9, vcc
	v_add_u32_e32 v9, 1, v7
	v_cmp_ge_u32_e32 vcc, v8, v6
	v_add_u32_e32 v8, 1, v5
	s_nop 0
	v_cndmask_b32_e32 v7, v7, v9, vcc
	v_add_u32_e32 v5, 1, v7
	v_mul_lo_u32 v6, v5, v6
	v_cmp_eq_u32_e32 vcc, v8, v6
.Ldv0_join:
	s_and_saveexec_b64 s[0:1], vcc
	s_cbranch_execz .LBB0_730
	buffer_wbl2 sc1
	s_waitcnt vmcnt(0)
	v_cmp_eq_u32_e32 vcc, 0xff, v4
	s_cbranch_vccz .Lrf0_slow
	v_mov_b32_e32 v6, s34
	v_add_co_u32_e32 v6, vcc, 0x2000, v6
	v_mov_b32_e32 v7, s35
	s_nop 0
	v_addc_co_u32_e32 v7, vcc, 0, v7, vcc
	v_mov_b32_e32 v8, 1
	global_atomic_add v[6:7], v8, off offset:1024
	global_atomic_add v[6:7], v8, off offset:1280
	global_atomic_add v[6:7], v8, off offset:1536
	global_atomic_add v[6:7], v8, off offset:1792
	global_atomic_add v[6:7], v8, off offset:2048
	global_atomic_add v[6:7], v8, off offset:2304
	global_atomic_add v[6:7], v8, off offset:2560
	global_atomic_add v[6:7], v8, off offset:2816
	s_or_b64 exec, exec, s[0:1]
	s_branch .Lrf0_join
